# S5: output GEMM remapped so workgroup bx takes its own tile (pm=bx, both column tiles); scan->out grid barrier becomes workgroup-local (state GEMM -> scan -> output GEMM now one phase)
# baseline (speedup 1.0000x reference)
.LBB0_326:
	s_or_b64 exec, exec, s[10:11]
	s_mov_b64 s[6:7], s[84:85]
	s_mov_b32 s3, s72
	v_mbcnt_lo_u32_b32 v0, -1, 0
	v_mbcnt_hi_u32_b32 v0, -1, v0
	s_getreg_b32 s2, hwreg(HW_REG_HW_ID, 0, 6)
	s_lshl_b32 s2, s2, 2
	s_and_b32 s2, s2, 0xfc
	s_add_i32 s2, s2, 0
	s_add_i32 s2, s2, 0x23400
	v_mov_b32_e32 v2, s2
	ds_read_b32 v2, v2
	s_waitcnt vmcnt(0) lgkmcnt(0)
	v_sub_u32_e32 v0, 0, v0
	s_waitcnt lgkmcnt(0)
	s_barrier
	v_readfirstlane_b32 s2, v2
	s_lshl_b32 s2, s2, 6
	s_nop 0
	v_cmp_eq_u32_e32 vcc, s2, v0
	s_mov_b64 s[4:5], exec
	s_cbranch_vccz .LBB0_394
	buffer_inv sc1
	s_waitcnt vmcnt(0)
	s_branch .LBB0_394
	v_mov_b32_e32 v0, s86
	s_load_dwordx2 s[6:7], s[6:7], 0x110
	s_getreg_b32 s2, hwreg(HW_REG_XCC_ID, 0, 4)
	ds_read_b32 v3, v0
	v_mov_b32_e32 v0, s87
	ds_read_b32 v2, v0
	s_and_b32 s2, s2, 15
	s_waitcnt lgkmcnt(0)
	v_cmp_ne_u32_e32 vcc, 0, v3
	s_cbranch_vccnz .LBB0_336
	s_add_u32 s8, s6, 0x4400
	s_addc_u32 s9, s7, 0
	s_add_u32 s10, s6, 0x4500
	s_addc_u32 s11, s7, 0
	s_add_u32 s12, s6, 0x4600
	s_addc_u32 s13, s7, 0
	s_add_u32 s14, s6, 0x4700
	s_addc_u32 s15, s7, 0
	s_add_u32 s16, s6, 0x4800
	s_addc_u32 s17, s7, 0
	s_add_u32 s18, s6, 0x4900
	s_addc_u32 s19, s7, 0
	s_add_u32 s20, s6, 0x4a00
	s_addc_u32 s21, s7, 0
	s_add_u32 s22, s6, 0x4b00
	s_addc_u32 s23, s7, 0
	s_add_u32 s24, s6, 0x4c00
	s_addc_u32 s25, s7, 0
	s_add_u32 s26, s6, 0x4d00
	s_addc_u32 s27, s7, 0
	s_add_u32 s28, s6, 0x4e00
	s_addc_u32 s29, s7, 0
	s_add_u32 s30, s6, 0x4f00
	s_addc_u32 s31, s7, 0
	s_add_u32 s34, s6, 0x5000
	s_addc_u32 s35, s7, 0
	s_add_u32 s36, s6, 0x5100
	s_addc_u32 s37, s7, 0
	s_add_u32 s38, s6, 0x5200
	s_addc_u32 s39, s7, 0
	s_add_u32 s40, s6, 0x5300
	s_addc_u32 s41, s7, 0
	s_mov_b32 s45, 0x400000
	s_branch .LBB0_331

.LBB0_394:
	s_or_b64 exec, exec, s[4:5]
	s_mov_b64 s[6:7], s[84:85]
	s_mov_b32 s24, s72
	s_lshl_b32 s25, s71, 1
	s_waitcnt lgkmcnt(0)
	s_barrier
	v_mbcnt_lo_u32_b32 v0, -1, 0
	v_mbcnt_hi_u32_b32 v0, -1, v0
	s_getreg_b32 s2, hwreg(HW_REG_HW_ID, 0, 6)
	s_lshl_b32 s2, s2, 2
	s_and_b32 s2, s2, 0xfc
	s_add_i32 s2, s2, 0
	s_add_i32 s2, s2, 0x23400
	v_mov_b32_e32 v2, s2
	ds_read_b32 v2, v2
	s_cmpk_gt_i32 s25, 0x1ff
	s_waitcnt lgkmcnt(0)
	v_readfirstlane_b32 s2, v2
	s_nop 1
	v_lshl_add_u32 v2, s2, 6, v0
	s_nop 0
	v_readfirstlane_b32 s3, v2
	s_cbranch_scc1 .LBB0_414
	v_lshlrev_b32_e32 v3, 4, v2
	v_add_u32_e32 v4, 0x2000, v3
	v_ashrrev_i32_e32 v5, 31, v4
	v_lshrrev_b32_e32 v5, 22, v5
	v_add_u32_e32 v5, v4, v5
	v_ashrrev_i32_e32 v10, 10, v5
	v_mul_i32_i24_e32 v5, 0x400, v10
	v_sub_u32_e32 v4, v4, v5
	v_lshrrev_b32_e32 v5, 4, v4
	v_bitop3_b32 v4, v5, v4, 32 bitop3:0x6c
	v_ashrrev_i32_e32 v5, 31, v4
	v_lshrrev_b32_e32 v5, 26, v5
	v_add_u32_e32 v5, v4, v5
	v_lshlrev_b32_e32 v6, 3, v10
	v_ashrrev_i32_e32 v11, 6, v5
	v_and_b32_e32 v6, -16, v6
	v_add_u32_e32 v6, v11, v6
	v_and_b32_e32 v7, 3, v11
	s_mov_b32 s2, 0x1ffffe0
	v_lshrrev_b32_e32 v8, 2, v6
	v_lshlrev_b32_e32 v9, 1, v6
	v_and_b32_e32 v5, 0xc0, v5
	v_and_or_b32 v7, v6, s2, v7
	v_and_b32_e32 v8, 4, v8
	v_and_b32_e32 v9, 24, v9
	v_sub_u32_e32 v4, v4, v5
	v_or3_b32 v7, v7, v8, v9
	v_lshlrev_b32_e32 v8, 5, v10
	v_ashrrev_i16_sdwa v4, v226, sext(v4) dst_sel:DWORD dst_unused:UNUSED_PAD src0_sel:DWORD src1_sel:BYTE_0
	v_and_b32_e32 v12, 32, v8
	v_bfe_i32 v13, v4, 0, 16
	v_mul_lo_u32 v7, v7, s79
	v_add_u32_e32 v4, v12, v13
	v_mul_lo_u32 v5, v6, s79
	v_add_lshl_u32 v180, v7, v4, 1
	v_add_lshl_u32 v182, v4, v5, 1
	v_bfe_i32 v4, v2, 27, 1
	v_lshrrev_b32_e32 v4, 22, v4
	v_add_u32_e32 v4, v3, v4
	v_and_b32_e32 v4, 0xfffffc00, v4
	s_load_dwordx2 s[4:5], s[6:7], 0x110
	s_load_dwordx2 s[8:9], s[6:7], 0xf0
	v_sub_u32_e32 v3, v3, v4
	v_lshrrev_b32_e32 v4, 4, v3
	v_ashrrev_i32_e32 v5, 31, v2
	v_bitop3_b32 v3, v4, v3, 32 bitop3:0x6c
	v_lshrrev_b32_e32 v5, 26, v5
	v_ashrrev_i32_e32 v4, 31, v3
	v_add_u32_e32 v2, v2, v5
	v_lshrrev_b32_e32 v4, 26, v4
	v_ashrrev_i32_e32 v15, 6, v2
	s_waitcnt lgkmcnt(0)
	s_add_u32 s26, s4, 0x11d00000
	v_add_u32_e32 v4, v3, v4
	v_lshlrev_b32_e32 v2, 3, v15
	s_addc_u32 s27, s5, 0
	v_ashrrev_i32_e32 v14, 6, v4
	v_and_b32_e32 v2, -16, v2
	s_add_u32 s28, s4, 0xb500000
	v_add_u32_e32 v2, v14, v2
	v_and_b32_e32 v5, 3, v14
	s_addc_u32 s29, s5, 0
	v_and_or_b32 v5, v2, s2, v5
	s_ashr_i32 s2, s25, 3
	s_lshl_b32 s6, s2, 2
	s_bfe_u32 s7, s25, 0x20001
	v_lshrrev_b32_e32 v6, 2, v2
	v_lshlrev_b32_e32 v7, 1, v2
	v_and_b32_e32 v4, 0xc0, v4
	s_or_b32 s43, s6, s7
	s_lshl_b32 s2, s2, 1
	s_and_b32 s6, s25, 1
	s_ashr_i32 s10, s3, 6
	v_and_b32_e32 v6, 4, v6
	v_and_b32_e32 v7, 24, v7
	v_sub_u32_e32 v3, v3, v4
	s_or_b32 s2, s2, s6
	s_ashr_i32 s11, s3, 8
	s_lshl_b32 s30, s10, 10
	v_or3_b32 v5, v5, v6, v7
	v_lshlrev_b32_e32 v6, 5, v15
	v_ashrrev_i16_sdwa v3, v226, sext(v3) dst_sel:DWORD dst_unused:UNUSED_PAD src0_sel:DWORD src1_sel:BYTE_0
	s_mul_i32 s7, s2, 0x50000
	v_and_b32_e32 v16, 32, v6
	v_bfe_i32 v17, v3, 0, 16
	s_mul_hi_i32 s6, s2, 0x50000
	s_add_u32 s18, s28, s7
	v_mul_lo_u32 v5, v5, s79
	v_add_u32_e32 v3, v16, v17
	s_addc_u32 s19, s29, s6
	s_add_i32 s31, s30, 0
	v_add_lshl_u32 v184, v5, v3, 1
	s_add_i32 m0, s31, 0x10000
	s_mul_i32 s13, s43, 0x50000
	global_load_lds_dwordx4 v184, s[18:19]
	s_add_i32 m0, s31, 0x12000
	s_add_u32 s6, s18, 0x28000
	global_load_lds_dwordx4 v180, s[18:19]
	s_addc_u32 s7, s19, 0
	s_add_i32 m0, s31, 0x14000
	s_mul_hi_i32 s12, s43, 0x50000
	global_load_lds_dwordx4 v184, s[6:7]
	s_add_i32 m0, s31, 0x16000
	s_add_u32 s16, s26, s13
	v_mul_lo_u32 v2, v2, s79
	s_addc_u32 s17, s27, s12
	s_add_i32 s34, s31, 0x2000
	v_add_lshl_u32 v186, v3, v2, 1
	global_load_lds_dwordx4 v180, s[6:7]
	s_mov_b32 m0, s31
	s_add_u32 s6, s16, 0x28000
	global_load_lds_dwordx4 v186, s[16:17]
	s_mov_b32 m0, s34
	s_addc_u32 s7, s17, 0
	s_add_i32 s35, s31, 0x4000
	global_load_lds_dwordx4 v182, s[16:17]
	s_mov_b32 m0, s35
	s_add_i32 s36, s31, 0x6000
	global_load_lds_dwordx4 v186, s[6:7]
	s_mov_b32 m0, s36
	v_mov_b32_e32 v185, v1
	global_load_lds_dwordx4 v182, s[6:7]
	v_mov_b32_e32 v181, v1
	v_mov_b32_e32 v187, v1
	v_mov_b32_e32 v183, v1
	s_cmp_eq_u32 s11, 1
	v_lshl_add_u64 v[8:9], s[18:19], 0, v[184:185]
	v_lshl_add_u64 v[6:7], s[18:19], 0, v[180:181]
	v_lshl_add_u64 v[2:3], s[16:17], 0, v[186:187]
	s_cselect_b64 s[6:7], -1, 0
	s_cmp_lg_u32 s11, 1
	v_lshl_add_u64 v[4:5], s[16:17], 0, v[182:183]
	s_cbranch_scc1 .LBB0_397
	s_barrier

.LBB0_400:
	s_add_i32 s40, s40, 1
	s_add_i32 s3, s25, s40
	s_cmpk_lt_i32 s40, 2
	s_cselect_b64 s[12:13], -1, 0
	s_cmpk_gt_i32 s40, 1
	s_cbranch_scc1 .LBB0_402
	s_ashr_i32 s4, s3, 3
	s_lshl_b32 s5, s4, 2
	s_bfe_u32 s14, s3, 0x20001
	s_lshl_b32 s4, s4, 1
	s_and_b32 s3, s3, 1
	s_or_b32 s41, s5, s14
	s_or_b32 s42, s4, s3
